# barrier flattened: last cross-XCD arriver bumps every per-XCC generation word directly, XCD leaders poll their own word (one relay hop removed)
# baseline (speedup 1.0000x reference)
.LBB0_873:
	s_or_b64 exec, exec, s[6:7]
	s_waitcnt vmcnt(0)
	v_readfirstlane_b32 s2, v3
	v_sub_u32_e32 v4, 0, v2
	s_mov_b64 s[6:7], 0
	v_add_u32_e32 v3, s2, v0
	v_cvt_f32_u32_e32 v0, v2
	v_readlane_b32 s2, v251, 54
	v_readlane_b32 s3, v251, 55
	s_add_u32 s2, s2, 0x2200
	s_addc_u32 s3, s3, 0
	v_rcp_iflag_f32_e32 v0, v0
	s_nop 0
	v_mul_f32_e32 v0, 0x4f7ffffe, v0
	v_cvt_u32_f32_e32 v0, v0
	v_mul_lo_u32 v4, v4, v0
	v_mul_hi_u32 v4, v0, v4
	v_add_u32_e32 v0, v0, v4
	v_mul_hi_u32 v0, v3, v0
	v_mul_lo_u32 v4, v0, v2
	v_sub_u32_e32 v4, v3, v4
	v_cmp_ge_u32_e32 vcc, v4, v2
	v_add_u32_e32 v5, 1, v0
	v_add_u32_e32 v3, 1, v3
	v_cndmask_b32_e32 v0, v0, v5, vcc
	v_sub_u32_e32 v5, v4, v2
	v_cndmask_b32_e32 v4, v4, v5, vcc
	v_cmp_ge_u32_e32 vcc, v4, v2
	v_add_u32_e32 v4, 1, v0
	s_nop 0
	v_cndmask_b32_e32 v0, v0, v4, vcc
	v_mul_lo_u32 v4, v2, v0
	v_add_u32_e32 v2, v4, v2
	v_cmp_ne_u32_e32 vcc, v3, v2
	v_mov_b64_e32 v[2:3], s[2:3]
	s_cbranch_vccnz .Lxb_notlast
	global_atomic_add v[2:3], v228, off
	global_atomic_add v[2:3], v228, off offset:256
	global_atomic_add v[2:3], v228, off offset:512
	global_atomic_add v[2:3], v228, off offset:768
	global_atomic_add v[2:3], v228, off offset:1024
	global_atomic_add v[2:3], v228, off offset:1280
	global_atomic_add v[2:3], v228, off offset:1536
	global_atomic_add v[2:3], v228, off offset:1792
	global_atomic_add v[2:3], v228, off offset:2048
	global_atomic_add v[2:3], v228, off offset:2304
	global_atomic_add v[2:3], v228, off offset:2560
	global_atomic_add v[2:3], v228, off offset:2816
	global_atomic_add v[2:3], v228, off offset:3072
	global_atomic_add v[2:3], v228, off offset:3328
	global_atomic_add v[2:3], v228, off offset:3584
	global_atomic_add v[2:3], v228, off offset:3840
.Lxb_notlast:
	s_and_saveexec_b64 s[2:3], vcc
	s_cbranch_execz .LBB0_885
	v_readlane_b32 s6, v252, 58
	v_readlane_b32 s7, v252, 59
	s_mov_b64 s[8:9], 0
	s_nop 3
	global_load_dword v2, v1, s[6:7] sc1
	s_waitcnt vmcnt(0)
	v_cmp_eq_u32_e32 vcc, v2, v0
	s_and_saveexec_b64 s[6:7], vcc
	s_cbranch_execz .LBB0_884
	s_mov_b32 s5, 1
	s_branch .LBB0_877

.LBB0_887:
	s_or_b64 exec, exec, s[2:3]
	s_mov_b64 s[2:3], exec
	v_mbcnt_lo_u32_b32 v0, s2, 0
	v_mbcnt_hi_u32_b32 v0, s3, v0
	v_cmp_eq_u32_e32 vcc, 0, v0
	s_waitcnt vmcnt(0)
	buffer_inv sc1
	s_and_saveexec_b64 s[6:7], vcc
	s_getpc_b64 s[98:99]
